# diff attention main loop: cross-half row-max exchange (mov/nop/permlane32_swap/max) moved into the rare rescale block; the all-lanes threshold test uses each lane's own half-row max
# speedup vs baseline: 1.0011x; 1.0011x over previous
; #define SBAR() __builtin_amdgcn_sched_barrier(0)
; __device__ __forceinline__ float max3f(float a, float b, float c) { float r; asm("v_max3_f32 %0, %1, %2, %3" : "=v"(r) : "v"(a), "v"(b), "v"(c)); return r; }
; #define VRD8(D0, L0, H0, L1, H1, L2, H2, L3, H3) do { L0 = tr_read<v_rd_off(D0, 0, 0)>(vb); H0 = tr_read<v_rd_off(D0, 0, 1)>(vb); L1 = tr_read<v_rd_off(D0, 1, 0)>(vb); H1 = tr_read<v_rd_off(D0, 1, 1)>(vb); \
;     L2 = tr_read<v_rd_off(D0, 2, 0)>(vb); H2 = tr_read<v_rd_off(D0, 2, 1)>(vb); L3 = tr_read<v_rd_off(D0, 3, 0)>(vb); H3 = tr_read<v_rd_off(D0, 3, 1)>(vb); } while (0)
; #define MMA4(OD, L0, H0, L1, H1, L2, H2, L3, H3) do { OD = __builtin_amdgcn_mfma_f32_32x32x16_bf16(pa0, PK(L0, H0), OD, 0, 0, 0); OD = __builtin_amdgcn_mfma_f32_32x32x16_bf16(pa1, PK(L1, H1), OD, 0, 0, 0); \
;     OD = __builtin_amdgcn_mfma_f32_32x32x16_bf16(pa2, PK(L2, H2), OD, 0, 0, 0); OD = __builtin_amdgcn_mfma_f32_32x32x16_bf16(pa3, PK(L3, H3), OD, 0, 0, 0); } while (0)
; __device__ __forceinline__ void pv_partial(f32x16* o, int vb, bf16x8 pa0, bf16x8 pa1, bf16x8 pa2, bf16x8 pa3, f32x16& p0, f32x16& p1, float& m_ref, f32x16& negm, float& alpha) {
;   s16x4 a0, a1, a2, a3, a4, a5, a6, a7, b0, b1, b2, b3, b4, b5, b6, b7;
;   VRD8(0, a0, a1, a2, a3, a4, a5, a6, a7);
;   VRD8(1, b0, b1, b2, b3, b4, b5, b6, b7);
;   asm volatile("s_waitcnt lgkmcnt(8)" ::: "memory"); SBAR();
;   MMA4(o[0], a0, a1, a2, a3, a4, a5, a6, a7);
;   float pmax = max3f(p0[0], p0[1], p1[0]), pmb = max3f(p0[2], p0[3], p1[1]);
;   pmax = max3f(pmax, p1[2], p1[3]);
; #pragma unroll
;   for (int r = 4; r < 16; r += 4) { pmax = max3f(pmax, p0[r], p0[r + 1]); pmb = max3f(pmb, p0[r + 2], p0[r + 3]); pmax = max3f(pmax, p1[r], p1[r + 1]); pmb = max3f(pmb, p1[r + 2], p1[r + 3]); }
;   pmax = max3f(pmax, pmb, pmb);
;   SBAR();
;   VRD8(2, a0, a1, a2, a3, a4, a5, a6, a7);
;   asm volatile("s_waitcnt lgkmcnt(8)" ::: "memory"); SBAR();
;   MMA4(o[1], b0, b1, b2, b3, b4, b5, b6, b7);
;   { auto rr = __builtin_amdgcn_permlane32_swap(__float_as_uint(pmax), __float_as_uint(pmax), false, false);
;     pmax = fmaxf(__uint_as_float(rr[0]), __uint_as_float(rr[1])); }
;   alpha = 1.f;
;   if (!__builtin_expect(__all(pmax <= THR), 1)) {
.LBB0_168:
	v_add_u32_e32 v201, s43, v199
	ds_read_b64_tr_b16 v[160:161], v201 offset:0
	ds_read_b64_tr_b16 v[162:163], v201 offset:0x800
	ds_read_b64_tr_b16 v[164:165], v201 offset:0x1000
	ds_read_b64_tr_b16 v[166:167], v201 offset:0x1800
	ds_read_b64_tr_b16 v[168:169], v201 offset:0x2000
	ds_read_b64_tr_b16 v[170:171], v201 offset:0x2800
	ds_read_b64_tr_b16 v[172:173], v201 offset:0x3000
	ds_read_b64_tr_b16 v[174:175], v201 offset:0x3800
	ds_read_b64_tr_b16 v[216:217], v201 offset:0x200
	ds_read_b64_tr_b16 v[218:219], v201 offset:0xa00
	ds_read_b64_tr_b16 v[220:221], v201 offset:0x1200
	ds_read_b64_tr_b16 v[222:223], v201 offset:0x1a00
	ds_read_b64_tr_b16 v[224:225], v201 offset:0x2200
	ds_read_b64_tr_b16 v[226:227], v201 offset:0x2a00
	ds_read_b64_tr_b16 v[228:229], v201 offset:0x3200
	ds_read_b64_tr_b16 v[230:231], v201 offset:0x3a00
	s_waitcnt lgkmcnt(8)
	s_nop 0
	v_mfma_f32_32x32x16_bf16 v[0:15], v[80:83], v[160:163], v[0:15]
	v_max3_f32 v160, v112, v113, v96
	v_max3_f32 v161, v114, v115, v97
	v_max3_f32 v160, v160, v98, v99
	v_max3_f32 v161, v161, v118, v119
	v_max3_f32 v160, v160, v116, v117
	v_mfma_f32_32x32x16_bf16 v[0:15], v[88:91], v[164:167], v[0:15]
	v_max3_f32 v160, v160, v100, v101
	v_max3_f32 v161, v161, v102, v103
	v_max3_f32 v160, v160, v120, v121
	v_max3_f32 v161, v161, v122, v123
	v_max3_f32 v160, v160, v104, v105
	v_mfma_f32_32x32x16_bf16 v[0:15], v[84:87], v[168:171], v[0:15]
	v_max3_f32 v161, v161, v106, v107
	v_max3_f32 v160, v160, v124, v125
	v_max3_f32 v161, v161, v126, v127
	v_max3_f32 v160, v160, v108, v109
	v_max3_f32 v161, v161, v110, v111
	v_mfma_f32_32x32x16_bf16 v[0:15], v[92:95], v[172:175], v[0:15]
	v_max3_f32 v206, v160, v161, v161
	ds_read_b64_tr_b16 v[172:173], v201 offset:0x400
	ds_read_b64_tr_b16 v[174:175], v201 offset:0xc00
	ds_read_b64_tr_b16 v[168:169], v201 offset:0x1400
	ds_read_b64_tr_b16 v[170:171], v201 offset:0x1c00
	ds_read_b64_tr_b16 v[164:165], v201 offset:0x2400
	ds_read_b64_tr_b16 v[166:167], v201 offset:0x2c00
	ds_read_b64_tr_b16 v[160:161], v201 offset:0x3400
	ds_read_b64_tr_b16 v[162:163], v201 offset:0x3c00
	s_waitcnt lgkmcnt(8)
	v_mfma_f32_32x32x16_bf16 v[48:63], v[80:83], v[216:219], v[48:63]
	v_cmp_ge_f32_e32 vcc, s76, v206
	v_mfma_f32_32x32x16_bf16 v[48:63], v[88:91], v[220:223], v[48:63]
	s_cmp_eq_u64 vcc, exec
	v_mfma_f32_32x32x16_bf16 v[48:63], v[84:87], v[224:227], v[48:63]
	v_mfma_f32_32x32x16_bf16 v[48:63], v[92:95], v[228:231], v[48:63]
	s_cbranch_scc0 .LBB0_187
	v_mov_b32_e32 v213, 1.0
	s_mov_b64 vcc, 0

; #define SBAR() __builtin_amdgcn_sched_barrier(0)
; __device__ __forceinline__ float max3f(float a, float b, float c) { float r; asm("v_max3_f32 %0, %1, %2, %3" : "=v"(r) : "v"(a), "v"(b), "v"(c)); return r; }
; #define VRD8(D0, L0, H0, L1, H1, L2, H2, L3, H3) do { L0 = tr_read<v_rd_off(D0, 0, 0)>(vb); H0 = tr_read<v_rd_off(D0, 0, 1)>(vb); L1 = tr_read<v_rd_off(D0, 1, 0)>(vb); H1 = tr_read<v_rd_off(D0, 1, 1)>(vb); \
;     L2 = tr_read<v_rd_off(D0, 2, 0)>(vb); H2 = tr_read<v_rd_off(D0, 2, 1)>(vb); L3 = tr_read<v_rd_off(D0, 3, 0)>(vb); H3 = tr_read<v_rd_off(D0, 3, 1)>(vb); } while (0)
; #define MMA4(OD, L0, H0, L1, H1, L2, H2, L3, H3) do { OD = __builtin_amdgcn_mfma_f32_32x32x16_bf16(pa0, PK(L0, H0), OD, 0, 0, 0); OD = __builtin_amdgcn_mfma_f32_32x32x16_bf16(pa1, PK(L1, H1), OD, 0, 0, 0); \
;     OD = __builtin_amdgcn_mfma_f32_32x32x16_bf16(pa2, PK(L2, H2), OD, 0, 0, 0); OD = __builtin_amdgcn_mfma_f32_32x32x16_bf16(pa3, PK(L3, H3), OD, 0, 0, 0); } while (0)
; __device__ __forceinline__ void pv_partial(f32x16* o, int vb, bf16x8 pa0, bf16x8 pa1, bf16x8 pa2, bf16x8 pa3, f32x16& p0, f32x16& p1, float& m_ref, f32x16& negm, float& alpha) {
;   s16x4 a0, a1, a2, a3, a4, a5, a6, a7, b0, b1, b2, b3, b4, b5, b6, b7;
;   VRD8(0, a0, a1, a2, a3, a4, a5, a6, a7);
;   VRD8(1, b0, b1, b2, b3, b4, b5, b6, b7);
;   asm volatile("s_waitcnt lgkmcnt(8)" ::: "memory"); SBAR();
;   MMA4(o[0], a0, a1, a2, a3, a4, a5, a6, a7);
;   float pmax = max3f(p0[0], p0[1], p1[0]), pmb = max3f(p0[2], p0[3], p1[1]);
;   pmax = max3f(pmax, p1[2], p1[3]);
; #pragma unroll
;   for (int r = 4; r < 16; r += 4) { pmax = max3f(pmax, p0[r], p0[r + 1]); pmb = max3f(pmb, p0[r + 2], p0[r + 3]); pmax = max3f(pmax, p1[r], p1[r + 1]); pmb = max3f(pmb, p1[r + 2], p1[r + 3]); }
;   pmax = max3f(pmax, pmb, pmb);
;   SBAR();
;   VRD8(2, a0, a1, a2, a3, a4, a5, a6, a7);
;   asm volatile("s_waitcnt lgkmcnt(8)" ::: "memory"); SBAR();
;   MMA4(o[1], b0, b1, b2, b3, b4, b5, b6, b7);
;   { auto rr = __builtin_amdgcn_permlane32_swap(__float_as_uint(pmax), __float_as_uint(pmax), false, false);
;     pmax = fmaxf(__uint_as_float(rr[0]), __uint_as_float(rr[1])); }
;   alpha = 1.f;
;   if (!__builtin_expect(__all(pmax <= THR), 1)) {
.LBB0_179:
	v_add_u32_e32 v217, s68, v199
	ds_read_b64_tr_b16 v[160:161], v217 offset:0
	ds_read_b64_tr_b16 v[162:163], v217 offset:0x800
	ds_read_b64_tr_b16 v[164:165], v217 offset:0x1000
	ds_read_b64_tr_b16 v[166:167], v217 offset:0x1800
	ds_read_b64_tr_b16 v[168:169], v217 offset:0x2000
	ds_read_b64_tr_b16 v[170:171], v217 offset:0x2800
	ds_read_b64_tr_b16 v[172:173], v217 offset:0x3000
	ds_read_b64_tr_b16 v[174:175], v217 offset:0x3800
	ds_read_b64_tr_b16 v[218:219], v217 offset:0x200
	ds_read_b64_tr_b16 v[220:221], v217 offset:0xa00
	ds_read_b64_tr_b16 v[222:223], v217 offset:0x1200
	ds_read_b64_tr_b16 v[224:225], v217 offset:0x1a00
	ds_read_b64_tr_b16 v[226:227], v217 offset:0x2200
	ds_read_b64_tr_b16 v[228:229], v217 offset:0x2a00
	ds_read_b64_tr_b16 v[230:231], v217 offset:0x3200
	ds_read_b64_tr_b16 v[232:233], v217 offset:0x3a00
	s_waitcnt lgkmcnt(8)
	s_nop 0
	v_mfma_f32_32x32x16_bf16 v[0:15], v[104:107], v[160:163], v[0:15]
	v_max3_f32 v160, v112, v113, v80
	v_max3_f32 v161, v114, v115, v81
	v_max3_f32 v160, v160, v82, v83
	v_max3_f32 v161, v161, v118, v119
	v_max3_f32 v160, v160, v116, v117
	v_mfma_f32_32x32x16_bf16 v[0:15], v[108:111], v[164:167], v[0:15]
	v_max3_f32 v160, v160, v84, v85
	v_max3_f32 v161, v161, v86, v87
	v_max3_f32 v160, v160, v120, v121
	v_max3_f32 v161, v161, v122, v123
	v_max3_f32 v160, v160, v88, v89
	v_mfma_f32_32x32x16_bf16 v[0:15], v[96:99], v[168:171], v[0:15]
	v_max3_f32 v161, v161, v90, v91
	v_max3_f32 v160, v160, v124, v125
	v_max3_f32 v161, v161, v126, v127
	v_max3_f32 v160, v160, v92, v93
	v_max3_f32 v161, v161, v94, v95
	v_mfma_f32_32x32x16_bf16 v[0:15], v[100:103], v[172:175], v[0:15]
	v_max3_f32 v206, v160, v161, v161
	ds_read_b64_tr_b16 v[172:173], v217 offset:0x400
	ds_read_b64_tr_b16 v[174:175], v217 offset:0xc00
	ds_read_b64_tr_b16 v[168:169], v217 offset:0x1400
	ds_read_b64_tr_b16 v[170:171], v217 offset:0x1c00
	ds_read_b64_tr_b16 v[164:165], v217 offset:0x2400
	ds_read_b64_tr_b16 v[166:167], v217 offset:0x2c00
	ds_read_b64_tr_b16 v[160:161], v217 offset:0x3400
	ds_read_b64_tr_b16 v[162:163], v217 offset:0x3c00
	s_waitcnt lgkmcnt(8)
	v_mfma_f32_32x32x16_bf16 v[48:63], v[104:107], v[218:221], v[48:63]
	v_cmp_ge_f32_e32 vcc, s76, v206
	v_mfma_f32_32x32x16_bf16 v[48:63], v[108:111], v[222:225], v[48:63]
	s_cmp_eq_u64 vcc, exec
	v_mfma_f32_32x32x16_bf16 v[48:63], v[96:99], v[226:229], v[48:63]
	v_mfma_f32_32x32x16_bf16 v[48:63], v[100:103], v[230:233], v[48:63]
	s_cbranch_scc0 .LBB0_188
	v_mov_b32_e32 v212, 1.0
	s_mov_b64 vcc, 0

; __device__ __forceinline__ void pv_partial(f32x16* o, int vb, bf16x8 pa0, bf16x8 pa1, bf16x8 pa2, bf16x8 pa3, f32x16& p0, f32x16& p1, float& m_ref, f32x16& negm, float& alpha) {
;     ...
;   { auto rr = __builtin_amdgcn_permlane32_swap(__float_as_uint(pmax), __float_as_uint(pmax), false, false);
;     pmax = fmaxf(__uint_as_float(rr[0]), __uint_as_float(rr[1])); }
;   alpha = 1.f;
;   if (!__builtin_expect(__all(pmax <= THR), 1)) {
;     const float dl = fmaxf(pmax, 0.f); m_ref += dl; alpha = __builtin_amdgcn_exp2f(-dl);
; #pragma unroll
;     for (int r = 0; r < 16; ++r) { p0[r] -= dl; p1[r] -= dl; negm[r] -= dl; }
;   }
.LBB0_187:
	v_mov_b32_e32 v207, v206
	s_nop 1
	v_permlane32_swap_b32_e32 v206, v207
	v_max_f32_e32 v213, v206, v207
	v_max_f32_e32 v206, v213, v213
	v_max_f32_e32 v206, 0, v206
	v_exp_f32_e64 v213, -v206
	v_pk_add_f32 v[112:113], v[112:113], v[206:207] op_sel_hi:[1,0] neg_lo:[0,1] neg_hi:[0,1]
	v_pk_add_f32 v[114:115], v[114:115], v[206:207] op_sel_hi:[1,0] neg_lo:[0,1] neg_hi:[0,1]
	v_pk_add_f32 v[116:117], v[116:117], v[206:207] op_sel_hi:[1,0] neg_lo:[0,1] neg_hi:[0,1]
	v_pk_add_f32 v[118:119], v[118:119], v[206:207] op_sel_hi:[1,0] neg_lo:[0,1] neg_hi:[0,1]
	v_pk_add_f32 v[120:121], v[120:121], v[206:207] op_sel_hi:[1,0] neg_lo:[0,1] neg_hi:[0,1]
	v_pk_add_f32 v[122:123], v[122:123], v[206:207] op_sel_hi:[1,0] neg_lo:[0,1] neg_hi:[0,1]
	v_pk_add_f32 v[124:125], v[124:125], v[206:207] op_sel_hi:[1,0] neg_lo:[0,1] neg_hi:[0,1]
	v_pk_add_f32 v[126:127], v[126:127], v[206:207] op_sel_hi:[1,0] neg_lo:[0,1] neg_hi:[0,1]
	v_sub_f32_e32 v111, v111, v206
	v_sub_f32_e32 v110, v110, v206
	v_sub_f32_e32 v109, v109, v206
	v_sub_f32_e32 v108, v108, v206
	v_sub_f32_e32 v107, v107, v206
	v_sub_f32_e32 v106, v106, v206
	v_sub_f32_e32 v105, v105, v206
	v_sub_f32_e32 v104, v104, v206
	v_sub_f32_e32 v103, v103, v206
	v_sub_f32_e32 v102, v102, v206
	v_sub_f32_e32 v101, v101, v206
	v_sub_f32_e32 v100, v100, v206
	v_sub_f32_e32 v99, v99, v206
	v_sub_f32_e32 v98, v98, v206
	v_sub_f32_e32 v97, v97, v206
	v_sub_f32_e32 v96, v96, v206
	v_sub_f32_e32 v79, v79, v206
	v_sub_f32_e32 v78, v78, v206
	v_sub_f32_e32 v77, v77, v206
	v_sub_f32_e32 v76, v76, v206
	v_sub_f32_e32 v75, v75, v206
	v_sub_f32_e32 v74, v74, v206
	v_sub_f32_e32 v73, v73, v206
	v_sub_f32_e32 v72, v72, v206
	v_sub_f32_e32 v71, v71, v206
	v_sub_f32_e32 v70, v70, v206
	v_sub_f32_e32 v69, v69, v206
	v_sub_f32_e32 v68, v68, v206
	v_sub_f32_e32 v67, v67, v206
	v_sub_f32_e32 v66, v66, v206
	v_sub_f32_e32 v65, v65, v206
	v_sub_f32_e32 v64, v64, v206
	v_cmp_gt_f32_e32 vcc, 1.0, v213
	s_branch .LBB0_170
.LBB0_188:
	v_mov_b32_e32 v207, v206
	s_nop 1
	v_permlane32_swap_b32_e32 v206, v207
	v_max_f32_e32 v212, v206, v207
	v_max_f32_e32 v206, v212, v212
	v_max_f32_e32 v206, 0, v206
	v_exp_f32_e64 v212, -v206
	v_pk_add_f32 v[112:113], v[112:113], v[206:207] op_sel_hi:[1,0] neg_lo:[0,1] neg_hi:[0,1]
	v_pk_add_f32 v[114:115], v[114:115], v[206:207] op_sel_hi:[1,0] neg_lo:[0,1] neg_hi:[0,1]
	v_pk_add_f32 v[116:117], v[116:117], v[206:207] op_sel_hi:[1,0] neg_lo:[0,1] neg_hi:[0,1]
	v_pk_add_f32 v[118:119], v[118:119], v[206:207] op_sel_hi:[1,0] neg_lo:[0,1] neg_hi:[0,1]
	v_pk_add_f32 v[120:121], v[120:121], v[206:207] op_sel_hi:[1,0] neg_lo:[0,1] neg_hi:[0,1]
	v_pk_add_f32 v[122:123], v[122:123], v[206:207] op_sel_hi:[1,0] neg_lo:[0,1] neg_hi:[0,1]
	v_pk_add_f32 v[124:125], v[124:125], v[206:207] op_sel_hi:[1,0] neg_lo:[0,1] neg_hi:[0,1]
	v_pk_add_f32 v[126:127], v[126:127], v[206:207] op_sel_hi:[1,0] neg_lo:[0,1] neg_hi:[0,1]
	v_sub_f32_e32 v95, v95, v206
	v_sub_f32_e32 v94, v94, v206
	v_sub_f32_e32 v93, v93, v206
	v_sub_f32_e32 v92, v92, v206
	v_sub_f32_e32 v91, v91, v206
	v_sub_f32_e32 v90, v90, v206
	v_sub_f32_e32 v89, v89, v206
	v_sub_f32_e32 v88, v88, v206
	v_sub_f32_e32 v87, v87, v206
	v_sub_f32_e32 v86, v86, v206
	v_sub_f32_e32 v85, v85, v206
	v_sub_f32_e32 v84, v84, v206
	v_sub_f32_e32 v83, v83, v206
	v_sub_f32_e32 v82, v82, v206
	v_sub_f32_e32 v81, v81, v206
	v_sub_f32_e32 v80, v80, v206
	v_sub_f32_e32 v79, v79, v206
	v_sub_f32_e32 v78, v78, v206
	v_sub_f32_e32 v77, v77, v206
	v_sub_f32_e32 v76, v76, v206
	v_sub_f32_e32 v75, v75, v206
	v_sub_f32_e32 v74, v74, v206
	v_sub_f32_e32 v73, v73, v206
	v_sub_f32_e32 v72, v72, v206
	v_sub_f32_e32 v71, v71, v206
	v_sub_f32_e32 v70, v70, v206
	v_sub_f32_e32 v69, v69, v206
	v_sub_f32_e32 v68, v68, v206
	v_sub_f32_e32 v67, v67, v206
	v_sub_f32_e32 v66, v66, v206
	v_sub_f32_e32 v65, v65, v206
	v_sub_f32_e32 v64, v64, v206
	v_cmp_gt_f32_e32 vcc, 1.0, v212
	s_branch .LBB0_181
